# dead scalar code removed in scans + one s_nop after the scan loops so later code keeps its byte phase mod 8
# baseline (speedup 1.0000x reference)
;     ...
; #pragma unroll 1
;     for (int s6 = 0; s6 < 42; s6 += 6) {
;         if (!scan_step<GDN, NT>(F, b, h, dir, wq, lane, L, s6 + 0, St, PEND, S, Oprev, A0, A2, F1, nofin, ko)) break;
;         if (!scan_step<GDN, NT>(F, b, h, dir, wq, lane, L, s6 + 1, St, PEND, S, Oprev, A1, A0, F0, nofin, ko)) break;
;         if (!scan_step<GDN, NT>(F, b, h, dir, wq, lane, L, s6 + 2, St, PEND, S, Oprev, A2, A1, F1, nofin, ko)) break;
;         if (!scan_step<GDN, NT>(F, b, h, dir, wq, lane, L, s6 + 3, St, PEND, S, Oprev, A0, A2, F0, nofin, ko)) break;
;         if (!scan_step<GDN, NT>(F, b, h, dir, wq, lane, L, s6 + 4, St, PEND, S, Oprev, A1, A0, F1, nofin, ko)) break;
;         if (!scan_step<GDN, NT>(F, b, h, dir, wq, lane, L, s6 + 5, St, PEND, S, Oprev, A2, A1, F0, nofin, ko)) break;
;     }
.LBB0_610:
	s_nop 0
	s_mov_b64 s[10:11], 0
